# stack + attention block loop: back-edge copy of the loop-top head with waits relaxed by the 5 outstanding stores
# speedup vs baseline: 1.0036x; 1.0036x over previous
.Lattn_join:
	v_and_b32_e32 v177, 0xffff0000, v90
	v_and_b32_e32 v179, 0xffff0000, v91
	v_add_f32_e32 v94, v94, v176
	v_lshlrev_b32_e32 v176, 16, v90
	v_lshlrev_b32_e32 v178, 16, v91
	v_mul_f32_e32 v183, v177, v177
	v_mul_f32_e32 v184, v179, v179
	v_and_b32_e32 v181, 0xffff0000, v92
	v_and_b32_e32 v186, 0xffff0000, v93
	v_fmac_f32_e32 v183, v176, v176
	v_fmac_f32_e32 v184, v178, v178
	v_lshlrev_b32_e32 v180, 16, v92
	v_lshlrev_b32_e32 v182, 16, v93
	v_add_f32_e32 v183, v183, v184
	v_mul_f32_e32 v184, v181, v181
	v_mul_f32_e32 v185, v186, v186
	v_fmac_f32_e32 v184, v180, v180
	v_fmac_f32_e32 v185, v182, v182
	v_add_f32_e32 v184, v184, v185
	v_add_f32_e32 v183, v183, v184
	v_add_f32_e32 v94, v94, v183
	v_mov_b32_e32 v183, v94
	s_nop 1
	v_permlane16_swap_b32_e32 v94, v183
	v_add_f32_e32 v94, v94, v183
	v_mov_b32_e32 v183, v94
	s_nop 1
	v_permlane32_swap_b32_e32 v94, v183
	v_add_f32_e32 v94, v94, v183
	v_fmamk_f32 v94, v94, 0x3c000000, v236
	v_rsq_f32_e32 v94, v94
	s_waitcnt lgkmcnt(0)
	s_barrier
	v_mul_f32_e32 v187, 0x3e0293ee, v94
	v_mul_f32_e32 v3, v187, v3
	v_mul_f32_e32 v2, v187, v2
	v_mul_f32_e32 v3, v15, v3
	v_mul_f32_e32 v2, v14, v2
	v_cvt_pk_bf16_f32 v94, v2, v3
	v_mul_f32_e32 v3, v187, v95
	v_mul_f32_e32 v2, v187, v5
	v_mul_f32_e32 v3, v17, v3
	v_mul_f32_e32 v2, v16, v2
	v_cvt_pk_bf16_f32 v95, v2, v3
	v_mul_f32_e32 v3, v187, v97
	v_mul_f32_e32 v2, v187, v96
	v_mul_f32_e32 v3, v19, v3
	v_mul_f32_e32 v2, v18, v2
	v_cvt_pk_bf16_f32 v96, v2, v3
	v_mul_f32_e32 v3, v187, v99
	v_mul_f32_e32 v2, v187, v98
	v_mul_f32_e32 v3, v21, v3
	v_mul_f32_e32 v2, v20, v2
	v_cvt_pk_bf16_f32 v97, v2, v3
	v_mul_f32_e32 v3, v187, v101
	v_mul_f32_e32 v2, v187, v100
	v_mul_f32_e32 v3, v23, v3
	v_mul_f32_e32 v2, v22, v2
	v_cvt_pk_bf16_f32 v98, v2, v3
	v_mul_f32_e32 v3, v187, v163
	v_mul_f32_e32 v2, v187, v162
	v_mul_f32_e32 v3, v25, v3
	v_mul_f32_e32 v2, v24, v2
	v_cvt_pk_bf16_f32 v99, v2, v3
	v_mul_f32_e32 v3, v187, v165
	v_mul_f32_e32 v2, v187, v164
	v_mul_f32_e32 v3, v27, v3
	v_mul_f32_e32 v2, v26, v2
	v_cvt_pk_bf16_f32 v100, v2, v3
	v_mul_f32_e32 v3, v187, v167
	v_mul_f32_e32 v2, v187, v166
	v_mul_f32_e32 v3, v29, v3
	v_mul_f32_e32 v2, v28, v2
	v_cvt_pk_bf16_f32 v101, v2, v3
	v_mul_f32_e32 v3, v187, v169
	v_mul_f32_e32 v2, v187, v168
	v_mul_f32_e32 v3, v31, v3
	v_mul_f32_e32 v2, v30, v2
	v_cvt_pk_bf16_f32 v162, v2, v3
	v_mul_f32_e32 v3, v187, v171
	v_mul_f32_e32 v2, v187, v170
	v_mul_f32_e32 v3, v33, v3
	v_mul_f32_e32 v2, v32, v2
	v_cvt_pk_bf16_f32 v163, v2, v3
	v_mul_f32_e32 v3, v187, v173
	v_mul_f32_e32 v2, v187, v172
	v_mul_f32_e32 v3, v35, v3
	v_mul_f32_e32 v2, v34, v2
	v_cvt_pk_bf16_f32 v164, v2, v3
	v_mul_f32_e32 v3, v187, v175
	v_mul_f32_e32 v2, v187, v174
	v_mul_f32_e32 v3, v37, v3
	v_mul_f32_e32 v2, v36, v2
	v_cvt_pk_bf16_f32 v165, v2, v3
	v_mul_f32_e32 v3, v187, v177
	v_mul_f32_e32 v2, v187, v176
	v_mul_f32_e32 v3, v39, v3
	v_mul_f32_e32 v2, v38, v2
	v_cvt_pk_bf16_f32 v166, v2, v3
	v_mul_f32_e32 v3, v187, v179
	v_mul_f32_e32 v2, v187, v178
	v_mul_f32_e32 v3, v41, v3
	v_mul_f32_e32 v2, v40, v2
	v_cvt_pk_bf16_f32 v167, v2, v3
	v_mul_f32_e32 v3, v187, v181
	v_mul_f32_e32 v2, v187, v180
	v_mul_f32_e32 v3, v43, v3
	v_mul_f32_e32 v2, v42, v2
	v_cvt_pk_bf16_f32 v168, v2, v3
	v_add_u32_e32 v3, s61, v161
	v_and_or_b32 v3, v3, s33, v143
	v_lshl_add_u32 v3, v3, 8, 0
	v_add_u32_e32 v5, v3, v126
	v_add_u32_e32 v169, v3, v127
	ds_read_b128 v[170:173], v5
	ds_read_b128 v[174:177], v169
	v_add_u32_e32 v5, v3, v128
	v_mul_f32_e32 v2, v187, v182
	v_add_u32_e32 v3, v3, v129
	ds_read_b128 v[178:181], v5
	ds_read_b128 v[182:185], v3
	s_lshl_b32 s50, s55, s58
	v_mul_f32_e32 v3, v187, v186
	s_add_i32 s52, s50, s56
	v_mul_f32_e32 v2, v44, v2
	v_mul_f32_e32 v3, v45, v3
	s_add_i32 s55, s55, 1
	v_cvt_pk_bf16_f32 v169, v2, v3
	s_setprio 1
	s_waitcnt lgkmcnt(3)
	v_mfma_f32_16x16x32_bf16 v[170:173], v[170:173], v[94:97], 0
	s_waitcnt lgkmcnt(2)
	v_mfma_f32_16x16x32_bf16 v[170:173], v[174:177], v[98:101], v[170:173]
	s_waitcnt lgkmcnt(1)
	v_mfma_f32_16x16x32_bf16 v[170:173], v[178:181], v[162:165], v[170:173]
	s_waitcnt lgkmcnt(0)
	v_mfma_f32_16x16x32_bf16 v[170:173], v[182:185], v[166:169], v[170:173]
	s_setprio 0
	v_add_u32_e32 v2, s61, v160
	v_and_or_b32 v2, v2, s33, v144
	v_lshl_add_u32 v2, v2, 8, 0
	v_add_u32_e32 v3, v2, v126
	v_add_u32_e32 v5, v2, v127
	ds_read_b128 v[174:177], v3
	ds_read_b128 v[178:181], v5
	v_add_u32_e32 v3, v2, v128
	v_add_u32_e32 v2, v2, v129
	ds_read_b128 v[182:185], v3
	ds_read_b128 v[186:189], v2
	s_setprio 1
	s_waitcnt lgkmcnt(3)
	v_mfma_f32_16x16x32_bf16 v[174:177], v[174:177], v[94:97], 0
	s_waitcnt lgkmcnt(2)
	v_mfma_f32_16x16x32_bf16 v[174:177], v[178:181], v[98:101], v[174:177]
	s_waitcnt lgkmcnt(1)
	v_mfma_f32_16x16x32_bf16 v[174:177], v[182:185], v[162:165], v[174:177]
	s_waitcnt lgkmcnt(0)
	v_mfma_f32_16x16x32_bf16 v[174:177], v[186:189], v[166:169], v[174:177]
	s_setprio 0
	v_add_u32_e32 v2, s61, v159
	v_and_or_b32 v2, v2, s33, v145
	v_lshl_add_u32 v2, v2, 8, 0
	v_add_u32_e32 v3, v2, v126
	v_add_u32_e32 v5, v2, v127
	ds_read_b128 v[178:181], v3
	ds_read_b128 v[182:185], v5
	v_add_u32_e32 v3, v2, v128
	v_add_u32_e32 v2, v2, v129
	ds_read_b128 v[186:189], v3
	ds_read_b128 v[190:193], v2
	s_setprio 1
	s_waitcnt lgkmcnt(3)
	v_mfma_f32_16x16x32_bf16 v[178:181], v[178:181], v[94:97], 0
	s_waitcnt lgkmcnt(2)
	v_mfma_f32_16x16x32_bf16 v[178:181], v[182:185], v[98:101], v[178:181]
	s_waitcnt lgkmcnt(1)
	v_mfma_f32_16x16x32_bf16 v[178:181], v[186:189], v[162:165], v[178:181]
	s_waitcnt lgkmcnt(0)
	v_mfma_f32_16x16x32_bf16 v[178:181], v[190:193], v[166:169], v[178:181]
	s_setprio 0
	v_add_u32_e32 v2, s61, v158
	v_and_or_b32 v2, v2, s33, v146
	v_lshl_add_u32 v2, v2, 8, 0
	v_add_u32_e32 v3, v2, v126
	v_add_u32_e32 v5, v2, v127
	ds_read_b128 v[182:185], v3
	ds_read_b128 v[186:189], v5
	v_add_u32_e32 v3, v2, v128
	v_add_u32_e32 v2, v2, v129
	ds_read_b128 v[190:193], v3
	ds_read_b128 v[194:197], v2
	s_setprio 1
	s_waitcnt lgkmcnt(3)
	v_mfma_f32_16x16x32_bf16 v[182:185], v[182:185], v[94:97], 0
	s_waitcnt lgkmcnt(2)
	v_mfma_f32_16x16x32_bf16 v[182:185], v[186:189], v[98:101], v[182:185]
	s_waitcnt lgkmcnt(1)
	v_mfma_f32_16x16x32_bf16 v[182:185], v[190:193], v[162:165], v[182:185]
	s_waitcnt lgkmcnt(0)
	v_mfma_f32_16x16x32_bf16 v[192:195], v[194:197], v[166:169], v[182:185]
	s_setprio 0
	v_add_u32_e32 v2, s61, v157
	v_and_or_b32 v2, v2, s33, v147
	v_lshl_add_u32 v2, v2, 8, 0
	v_add_u32_e32 v3, v2, v126
	v_add_u32_e32 v5, v2, v127
	ds_read_b128 v[182:185], v3
	ds_read_b128 v[186:189], v5
	v_add_u32_e32 v3, v2, v128
	v_add_u32_e32 v2, v2, v129
	ds_read_b128 v[196:199], v3
	ds_read_b128 v[200:203], v2
	s_setprio 1
	s_waitcnt lgkmcnt(3)
	v_mfma_f32_16x16x32_bf16 v[182:185], v[182:185], v[94:97], 0
	s_waitcnt lgkmcnt(2)
	v_mfma_f32_16x16x32_bf16 v[182:185], v[186:189], v[98:101], v[182:185]
	s_waitcnt lgkmcnt(1)
	v_mfma_f32_16x16x32_bf16 v[182:185], v[196:199], v[162:165], v[182:185]
	s_waitcnt lgkmcnt(0)
	v_mfma_f32_16x16x32_bf16 v[196:199], v[200:203], v[166:169], v[182:185]
	s_setprio 0
	v_add_u32_e32 v2, s61, v156
	v_and_or_b32 v2, v2, s33, v148
	v_lshl_add_u32 v2, v2, 8, 0
	v_add_u32_e32 v3, v2, v126
	v_add_u32_e32 v5, v2, v127
	ds_read_b128 v[182:185], v3
	ds_read_b128 v[186:189], v5
	v_add_u32_e32 v3, v2, v128
	v_add_u32_e32 v2, v2, v129
	ds_read_b128 v[200:203], v3
	ds_read_b128 v[204:207], v2
	s_setprio 1
	s_waitcnt lgkmcnt(3)
	v_mfma_f32_16x16x32_bf16 v[182:185], v[182:185], v[94:97], 0
	s_waitcnt lgkmcnt(2)
	v_mfma_f32_16x16x32_bf16 v[182:185], v[186:189], v[98:101], v[182:185]
	s_waitcnt lgkmcnt(1)
	v_mfma_f32_16x16x32_bf16 v[182:185], v[200:203], v[162:165], v[182:185]
	s_waitcnt lgkmcnt(0)
	v_mfma_f32_16x16x32_bf16 v[200:203], v[204:207], v[166:169], v[182:185]
	s_setprio 0
	v_add_u32_e32 v2, s61, v155
	v_and_or_b32 v2, v2, s33, v149
	v_lshl_add_u32 v2, v2, 8, 0
	v_add_u32_e32 v3, v2, v126
	v_add_u32_e32 v5, v2, v127
	ds_read_b128 v[182:185], v3
	ds_read_b128 v[186:189], v5
	v_add_u32_e32 v3, v2, v128
	v_add_u32_e32 v2, v2, v129
	ds_read_b128 v[204:207], v3
	ds_read_b128 v[208:211], v2
	s_setprio 1
	s_waitcnt lgkmcnt(3)
	v_mfma_f32_16x16x32_bf16 v[182:185], v[182:185], v[94:97], 0
	s_waitcnt lgkmcnt(2)
	v_mfma_f32_16x16x32_bf16 v[182:185], v[186:189], v[98:101], v[182:185]
	s_waitcnt lgkmcnt(1)
	v_mfma_f32_16x16x32_bf16 v[182:185], v[204:207], v[162:165], v[182:185]
	s_waitcnt lgkmcnt(0)
	v_mfma_f32_16x16x32_bf16 v[204:207], v[208:211], v[166:169], v[182:185]
	s_setprio 0
	v_add_u32_e32 v2, s61, v154
	v_and_or_b32 v2, v2, s33, v150
	v_lshl_add_u32 v2, v2, 8, 0
	v_add_u32_e32 v3, v2, v126
	v_add_u32_e32 v5, v2, v127
	ds_read_b128 v[182:185], v3
	ds_read_b128 v[186:189], v5
	v_add_u32_e32 v3, v2, v128
	v_add_u32_e32 v2, v2, v129
	ds_read_b128 v[208:211], v3
	ds_read_b128 v[212:215], v2
	s_setprio 1
	s_waitcnt lgkmcnt(3)
	v_mfma_f32_16x16x32_bf16 v[182:185], v[182:185], v[94:97], 0
	s_waitcnt lgkmcnt(2)
	v_mfma_f32_16x16x32_bf16 v[182:185], v[186:189], v[98:101], v[182:185]
	s_waitcnt lgkmcnt(1)
	v_mfma_f32_16x16x32_bf16 v[182:185], v[208:211], v[162:165], v[182:185]
	s_waitcnt lgkmcnt(0)
	v_mfma_f32_16x16x32_bf16 v[208:211], v[212:215], v[166:169], v[182:185]
	s_setprio 0
	v_add_u32_e32 v2, s61, v153
	v_and_or_b32 v2, v2, s33, v151
	v_lshl_add_u32 v2, v2, 8, 0
	v_add_u32_e32 v3, v2, v126
	v_add_u32_e32 v5, v2, v127
	ds_read_b128 v[182:185], v3
	ds_read_b128 v[186:189], v5
	v_add_u32_e32 v3, v2, v128
	v_add_u32_e32 v2, v2, v129
	ds_read_b128 v[212:215], v3
	ds_read_b128 v[216:219], v2
	s_setprio 1
	s_waitcnt lgkmcnt(3)
	v_mfma_f32_16x16x32_bf16 v[94:97], v[182:185], v[94:97], 0
	s_waitcnt lgkmcnt(2)
	v_mfma_f32_16x16x32_bf16 v[94:97], v[186:189], v[98:101], v[94:97]
	s_waitcnt lgkmcnt(1)
	v_mfma_f32_16x16x32_bf16 v[94:97], v[212:215], v[162:165], v[94:97]
	s_waitcnt lgkmcnt(0)
	v_mfma_f32_16x16x32_bf16 v[94:97], v[216:219], v[166:169], v[94:97]
	s_setprio 0
	s_cmp_eq_u32 s60, 0
	v_exp_f32_e32 v2, v170
	s_cselect_b64 s[50:51], -1, 0
	v_exp_f32_e32 v3, v171
	s_and_b64 s[64:65], s[14:15], s[50:51]
	s_or_b64 s[66:67], s[64:65], s[12:13]
	v_cndmask_b32_e64 v99, v2, 0, s[66:67]
	s_or_b64 s[66:67], s[64:65], s[16:17]
	v_cndmask_b32_e64 v163, v3, 0, s[66:67]
	v_exp_f32_e32 v3, v172
	v_exp_f32_e32 v5, v173
	s_or_b64 s[66:67], s[64:65], s[18:19]
	s_or_b64 s[64:65], s[64:65], s[20:21]
	v_cndmask_b32_e64 v165, v3, 0, s[66:67]
	v_exp_f32_e32 v3, v174
	v_cndmask_b32_e64 v169, v5, 0, s[64:65]
	v_exp_f32_e32 v5, v175
	s_and_b64 s[64:65], s[22:23], s[50:51]
	v_cndmask_b32_e64 v187, v3, 0, s[64:65]
	v_exp_f32_e32 v3, v176
	v_cndmask_b32_e64 v188, v5, 0, s[64:65]
	v_exp_f32_e32 v5, v177
	v_add_f32_e32 v2, 0, v99
	v_cndmask_b32_e64 v189, v3, 0, s[64:65]
	v_exp_f32_e32 v3, v178
	v_cndmask_b32_e64 v190, v5, 0, s[64:65]
	v_exp_f32_e32 v5, v179
	s_and_b64 s[64:65], s[24:25], s[50:51]
	v_cndmask_b32_e64 v179, v3, 0, s[64:65]
	v_exp_f32_e32 v3, v180
	v_cndmask_b32_e64 v180, v5, 0, s[64:65]
	v_exp_f32_e32 v5, v181
	v_add_f32_e32 v2, v163, v2
	v_cndmask_b32_e64 v181, v3, 0, s[64:65]
	v_exp_f32_e32 v3, v192
	v_cndmask_b32_e64 v182, v5, 0, s[64:65]
	v_exp_f32_e32 v5, v193
	s_and_b64 s[64:65], s[26:27], s[50:51]
	v_cndmask_b32_e64 v183, v3, 0, s[64:65]
	v_exp_f32_e32 v3, v194
	v_cndmask_b32_e64 v184, v5, 0, s[64:65]
	v_exp_f32_e32 v5, v195
	v_add_f32_e32 v2, v165, v2
	v_cndmask_b32_e64 v185, v3, 0, s[64:65]
	v_exp_f32_e32 v3, v196
	v_cndmask_b32_e64 v186, v5, 0, s[64:65]
	v_exp_f32_e32 v5, v197
	s_and_b64 s[64:65], s[28:29], s[50:51]
	v_cndmask_b32_e64 v171, v3, 0, s[64:65]
	v_exp_f32_e32 v3, v198
	v_cndmask_b32_e64 v172, v5, 0, s[64:65]
	v_exp_f32_e32 v5, v199
	v_add_f32_e32 v2, v169, v2
	v_add_f32_e32 v2, v2, v187
	v_add_f32_e32 v2, v188, v2
	v_cndmask_b32_e64 v173, v3, 0, s[64:65]
	v_exp_f32_e32 v3, v200
	v_add_f32_e32 v2, v189, v2
	v_cndmask_b32_e64 v174, v5, 0, s[64:65]
	v_exp_f32_e32 v5, v201
	v_add_f32_e32 v2, v190, v2
	v_add_f32_e32 v2, v2, v179
	s_and_b64 s[64:65], s[30:31], s[50:51]
	v_add_f32_e32 v2, v180, v2
	v_cndmask_b32_e64 v175, v3, 0, s[64:65]
	v_exp_f32_e32 v3, v202
	v_add_f32_e32 v2, v181, v2
	v_cndmask_b32_e64 v176, v5, 0, s[64:65]
	v_exp_f32_e32 v5, v203
	v_add_f32_e32 v2, v182, v2
	v_add_f32_e32 v2, v2, v183
	v_add_f32_e32 v2, v184, v2
	v_cndmask_b32_e64 v177, v3, 0, s[64:65]
	v_exp_f32_e32 v3, v204
	v_add_f32_e32 v2, v185, v2
	v_cndmask_b32_e64 v178, v5, 0, s[64:65]
	v_exp_f32_e32 v5, v205
	v_add_f32_e32 v2, v186, v2
	v_add_f32_e32 v2, v2, v171
	s_and_b64 s[64:65], s[34:35], s[50:51]
	v_add_f32_e32 v2, v172, v2
	v_cndmask_b32_e64 v100, v3, 0, s[64:65]
	v_exp_f32_e32 v3, v206
	v_add_f32_e32 v2, v173, v2
	v_cndmask_b32_e64 v101, v5, 0, s[64:65]
	v_exp_f32_e32 v5, v207
	v_add_f32_e32 v2, v174, v2
	v_add_f32_e32 v2, v2, v175
	v_add_f32_e32 v2, v176, v2
	v_cndmask_b32_e64 v162, v3, 0, s[64:65]
	v_exp_f32_e32 v3, v208
	v_add_f32_e32 v2, v177, v2
	v_cndmask_b32_e64 v164, v5, 0, s[64:65]
	v_exp_f32_e32 v5, v209
	v_add_f32_e32 v2, v178, v2
	v_add_f32_e32 v2, v2, v100
	s_and_b64 s[64:65], s[36:37], s[50:51]
	v_add_f32_e32 v2, v101, v2
	v_cndmask_b32_e64 v166, v3, 0, s[64:65]
	v_exp_f32_e32 v3, v210
	v_add_f32_e32 v2, v162, v2
	v_cndmask_b32_e64 v167, v5, 0, s[64:65]
	v_exp_f32_e32 v5, v211
	v_add_f32_e32 v2, v164, v2
	v_add_f32_e32 v2, v2, v166
	v_add_f32_e32 v2, v167, v2
	v_cndmask_b32_e64 v168, v3, 0, s[64:65]
	v_add_f32_e32 v2, v168, v2
	v_cndmask_b32_e64 v170, v5, 0, s[64:65]
	v_add_f32_e32 v3, v170, v2
	v_exp_f32_e32 v2, v94
	v_exp_f32_e32 v5, v95
	s_and_b64 s[50:51], s[38:39], s[50:51]
	s_or_b64 s[64:65], s[50:51], s[10:11]
	v_cndmask_b32_e64 v2, v2, 0, s[64:65]
	s_or_b64 s[64:65], s[50:51], s[40:41]
	v_add_f32_e32 v94, v3, v2
	v_cndmask_b32_e64 v3, v5, 0, s[64:65]
	v_exp_f32_e32 v5, v96
	v_exp_f32_e32 v95, v97
	s_or_b64 s[64:65], s[50:51], s[42:43]
	v_add_f32_e32 v94, v3, v94
	v_cndmask_b32_e64 v5, v5, 0, s[64:65]
	s_or_b64 s[50:51], s[50:51], s[44:45]
	v_add_f32_e32 v94, v5, v94
	v_cndmask_b32_e64 v98, v95, 0, s[50:51]
	v_add_f32_e32 v94, v98, v94
	v_mov_b32_e32 v95, v94
	s_nop 1
	v_permlane16_swap_b32_e32 v94, v95
	v_add_f32_e32 v96, v94, v95
	s_cmp_lt_u32 s55, s59
	v_mov_b32_e32 v97, v96
	s_cselect_b64 s[50:51], -1, 0
	s_cmp_ge_u32 s55, s59
	v_permlane32_swap_b32_e32 v96, v97
	s_cbranch_scc1 .LBB0_587
	s_add_i32 s53, s52, s57
	s_ashr_i32 s63, s53, 31
	s_add_u32 s64, s46, s53
	s_addc_u32 s65, s47, s63
	v_lshl_add_u64 v[46:47], s[64:65], 0, v[110:111]
	v_lshl_add_u64 v[54:55], s[64:65], 0, v[112:113]
	v_lshl_add_u64 v[62:63], s[64:65], 0, v[114:115]
	v_lshl_add_u64 v[70:71], s[64:65], 0, v[116:117]
	v_lshl_add_u64 v[78:79], s[64:65], 0, v[118:119]
	v_mad_u64_u32 v[50:51], s[66:67], v46, s77, v[108:109]
	v_mad_u64_u32 v[58:59], s[66:67], v54, s77, v[108:109]
	v_mad_u64_u32 v[66:67], s[66:67], v62, s77, v[108:109]
	v_mad_u64_u32 v[74:75], s[66:67], v70, s77, v[108:109]
	v_mad_u64_u32 v[90:91], s[64:65], v78, s77, v[104:105]
	v_mad_i32_i24 v51, v47, s77, v51
	v_mad_i32_i24 v59, v55, s77, v59
	v_mad_i32_i24 v67, v63, s77, v67
	v_mad_i32_i24 v75, v71, s77, v75
	v_mad_i32_i24 v91, v79, s77, v91
	global_load_dwordx4 v[46:49], v[50:51], off offset:1024
	s_nop 0
	global_load_dwordx4 v[50:53], v[50:51], off offset:2048
	s_nop 0
	global_load_dwordx4 v[54:57], v[58:59], off offset:1024
	s_nop 0
	global_load_dwordx4 v[58:61], v[58:59], off offset:2048
	s_nop 0
	global_load_dwordx4 v[62:65], v[66:67], off offset:1024
	s_nop 0
	global_load_dwordx4 v[66:69], v[66:67], off offset:2048
	s_nop 0
	global_load_dwordx4 v[70:73], v[74:75], off offset:1024
	s_nop 0
	global_load_dwordx4 v[74:77], v[74:75], off offset:2048
	s_nop 0
	global_load_dwordx4 v[78:81], v[90:91], off
	global_load_dwordx4 v[82:85], v[90:91], off offset:64
	global_load_dwordx4 v[86:89], v[90:91], off offset:128
	s_nop 0
	global_load_dwordx4 v[90:93], v[90:91], off offset:192

.Lattn_top_be:
	s_andn2_b64 vcc, exec, s[50:51]
	s_waitcnt vmcnt(8)
	v_and_b32_e32 v3, 0xffff0000, v78
	v_and_b32_e32 v95, 0xffff0000, v79
	v_lshlrev_b32_e32 v2, 16, v78
	v_lshlrev_b32_e32 v5, 16, v79
	v_mul_f32_e32 v94, v3, v3
	v_mul_f32_e32 v100, v95, v95
	v_and_b32_e32 v97, 0xffff0000, v80
	v_and_b32_e32 v99, 0xffff0000, v81
	v_fmac_f32_e32 v94, v2, v2
	v_fmac_f32_e32 v100, v5, v5
	v_lshlrev_b32_e32 v96, 16, v80
	v_lshlrev_b32_e32 v98, 16, v81
	v_add_f32_e32 v94, v94, v100
	v_mul_f32_e32 v100, v97, v97
	v_mul_f32_e32 v101, v99, v99
	v_fmac_f32_e32 v100, v96, v96
	v_fmac_f32_e32 v101, v98, v98
	v_add_f32_e32 v100, v100, v101
	s_waitcnt vmcnt(7)
	v_and_b32_e32 v101, 0xffff0000, v82
	v_and_b32_e32 v163, 0xffff0000, v83
	v_add_f32_e32 v94, v94, v100
	v_lshlrev_b32_e32 v100, 16, v82
	v_lshlrev_b32_e32 v162, 16, v83
	v_mul_f32_e32 v168, v101, v101
	v_mul_f32_e32 v169, v163, v163
	v_and_b32_e32 v165, 0xffff0000, v84
	v_and_b32_e32 v167, 0xffff0000, v85
	v_fmac_f32_e32 v168, v100, v100
	v_fmac_f32_e32 v169, v162, v162
	v_lshlrev_b32_e32 v164, 16, v84
	v_lshlrev_b32_e32 v166, 16, v85
	v_add_f32_e32 v168, v168, v169
	v_mul_f32_e32 v169, v165, v165
	v_mul_f32_e32 v170, v167, v167
	v_fmac_f32_e32 v169, v164, v164
	v_fmac_f32_e32 v170, v166, v166
	v_add_f32_e32 v169, v169, v170
	v_add_f32_e32 v168, v168, v169
	s_waitcnt vmcnt(6)
	v_and_b32_e32 v169, 0xffff0000, v86
	v_and_b32_e32 v171, 0xffff0000, v87
	v_add_f32_e32 v94, v94, v168
	v_lshlrev_b32_e32 v168, 16, v86
	v_lshlrev_b32_e32 v170, 16, v87
	v_mul_f32_e32 v176, v169, v169
	v_mul_f32_e32 v177, v171, v171
	v_and_b32_e32 v173, 0xffff0000, v88
	v_and_b32_e32 v175, 0xffff0000, v89
	v_fmac_f32_e32 v176, v168, v168
	v_fmac_f32_e32 v177, v170, v170
	v_lshlrev_b32_e32 v172, 16, v88
	v_lshlrev_b32_e32 v174, 16, v89
	v_add_f32_e32 v176, v176, v177
	v_mul_f32_e32 v177, v173, v173
	v_mul_f32_e32 v178, v175, v175
	v_fmac_f32_e32 v177, v172, v172
	v_fmac_f32_e32 v178, v174, v174
	v_add_f32_e32 v177, v177, v178
	v_add_f32_e32 v176, v176, v177
	s_waitcnt vmcnt(5)
	s_branch .Lattn_join
